# attention: beta and 1-beta computed from e=2^z as e*r and r (r=1/(1+e)) instead of 2^-|z| plus sign selects
# speedup vs baseline: 1.0064x; 1.0064x over previous
; #define LAS __attribute__((address_space(3)))
; __device__ __forceinline__ void attn_unit(LAS unsigned char* lds, const bf16_t* Qm, const bf16_t* Km, const bf16_t* VT, const bf16_t* GBm, bf16_t* YB, int b, int hp, int qb) {
;     ...
;             f32x4 s[4];
; #pragma unroll
;             for (int rb = 0; rb < 4; ++rb) {
;                 const int c = rb >> 1, e = rb & 1;
;                 const int kl = 32 * c + (fr >> 2) * 8 + e * 4 + (fr & 3);
;                 s[rb] = (f32x4){0.f, 0.f, 0.f, 0.f};
; #pragma unroll
;                 for (int ks = 0; ks < 4; ++ks) {
;                     const bf16x8 a = *(const LAS bf16x8*)(KL + kl * 272 + (ks * 32 + fq * 8) * 2);
;                     s[rb] = __builtin_amdgcn_mfma_f32_16x16x32_bf16(a, qf[ks], s[rb], 0, 0, 0);
;                 }
;             }
;             const int qi = qw + fr;
;             float be[2][8], om[2][8];
; #pragma unroll
;             for (int c = 0; c < 2; ++c)
; #pragma unroll
;                 for (int i = 0; i < 8; ++i) {
;                     const float z = s[2 * c + (i >> 2)][i & 3];
;                     const int key = k0 + 32 * c + 8 * fq + i;
;                     const float e = __builtin_amdgcn_exp2f(-fabsf(z));
;                     const float r = __builtin_amdgcn_rcpf(1.0f + e);
;                     const bool pos = z >= 0.f, valid = key < qi;
;                     be[c][i] = valid ? (pos ? r : e * r) : 0.f;
;                     om[c][i] = valid ? (pos ? e * r : r) : 1.f;
;                 }
.LBB0_519:
	s_add_i32 s12, s56, 64
	v_cmp_lt_u32_e32 vcc, s12, v109
	s_and_saveexec_b64 s[58:59], vcc
	s_cbranch_execz .LBB0_522
	v_cmp_eq_f32_e32 vcc, 0, v96
	s_cmp_eq_u64 vcc, exec
	s_cbranch_scc1 .LBB0_522
	ds_read_b128 v[120:123], v116
	ds_read_b128 v[124:127], v116 offset:64
	ds_read_b128 v[128:131], v116 offset:1088
	ds_read_b128 v[132:135], v116 offset:1152
	v_add_u32_e32 v99, s56, v108
	v_add_u32_e32 v103, 64, v99
	s_waitcnt lgkmcnt(3)
	v_mfma_f32_16x16x32_bf16 v[120:123], v[120:123], v[0:3], 0
	s_waitcnt lgkmcnt(2)
	v_mfma_f32_16x16x32_bf16 v[120:123], v[124:127], v[4:7], v[120:123]
	ds_read_b128 v[124:127], v116 offset:128
	ds_read_b128 v[136:139], v116 offset:192
	s_waitcnt lgkmcnt(3)
	v_mfma_f32_16x16x32_bf16 v[128:131], v[128:131], v[0:3], 0
	s_waitcnt lgkmcnt(1)
	v_mfma_f32_16x16x32_bf16 v[120:123], v[124:127], v[8:11], v[120:123]
	ds_read_b128 v[124:127], v116 offset:1216
	ds_read_b128 v[140:143], v116 offset:1280
	ds_read_b128 v[144:147], v116 offset:8704
	ds_read_b128 v[148:151], v116 offset:8768
	v_mfma_f32_16x16x32_bf16 v[128:131], v[132:135], v[4:7], v[128:131]
	ds_read_b128 v[132:135], v116 offset:8832
	ds_read_b128 v[152:155], v116 offset:8896
	ds_read_b128 v[156:159], v116 offset:9792
	ds_read_b128 v[160:163], v116 offset:9856
	s_waitcnt lgkmcnt(8)
	v_mfma_f32_16x16x32_bf16 v[120:123], v[136:139], v[12:15], v[120:123]
	ds_read_b128 v[136:139], v116 offset:9920
	ds_read_b128 v[164:167], v116 offset:9984
	s_waitcnt lgkmcnt(9)
	v_mfma_f32_16x16x32_bf16 v[124:127], v[124:127], v[8:11], v[128:131]
	s_nop 3
	v_exp_f32_e32 v97, v120
	s_nop 0
	v_add_f32_e32 v101, 1.0, v97
	s_waitcnt lgkmcnt(7)
	v_mfma_f32_16x16x32_bf16 v[128:131], v[144:147], v[0:3], 0
	v_rcp_f32_e32 v101, v101
	s_nop 0
	v_mul_f32_e32 v97, v97, v101
	s_waitcnt lgkmcnt(6)
	v_mfma_f32_16x16x32_bf16 v[128:131], v[148:151], v[4:7], v[128:131]
	v_mov_b32_e32 v120, v97
	v_mov_b32_e32 v97, v101
	v_cmp_lt_u32_e32 vcc, v103, v111
	v_mfma_f32_16x16x32_bf16 v[124:127], v[140:143], v[12:15], v[124:127]
	v_exp_f32_e32 v140, v121
	v_exp_f32_e32 v141, v122
	v_cndmask_b32_e32 v101, 0, v120, vcc
	s_waitcnt lgkmcnt(5)
	v_mfma_f32_16x16x32_bf16 v[128:131], v[132:135], v[8:11], v[128:131]
	v_add_f32_e32 v103, 1.0, v140
	v_rcp_f32_e32 v103, v103
	v_add_u32_e32 v120, 0x41, v99
	s_waitcnt lgkmcnt(3)
	v_mfma_f32_16x16x32_bf16 v[132:135], v[156:159], v[0:3], 0
	v_cmp_lt_u32_e64 s[12:13], v120, v111
	v_add_f32_e32 v120, 1.0, v141
	v_rcp_f32_e32 v120, v120
	s_waitcnt lgkmcnt(2)
	v_mfma_f32_16x16x32_bf16 v[132:135], v[160:163], v[4:7], v[132:135]
	v_cndmask_b32_e32 v97, 1.0, v97, vcc
	v_mul_f32_e32 v140, v140, v103
	s_waitcnt lgkmcnt(1)
	v_mfma_f32_16x16x32_bf16 v[132:135], v[136:139], v[8:11], v[132:135]
	v_exp_f32_e32 v136, v123
	v_exp_f32_e32 v137, v124
	v_cndmask_b32_e64 v142, 0, v140, s[12:13]
	v_add_u32_e32 v121, 0x42, v99
	v_mul_f32_e32 v140, v141, v120
	v_cndmask_b32_e64 v103, 1.0, v103, s[12:13]
	v_cmp_lt_u32_e64 s[12:13], v121, v111
	v_add_f32_e32 v121, 1.0, v136
	s_nop 0
	v_cndmask_b32_e64 v143, 0, v140, s[12:13]
	v_add_u32_e32 v122, 0x43, v99
	v_rcp_f32_e32 v121, v121
	v_cndmask_b32_e64 v120, 1.0, v120, s[12:13]
	v_cmp_lt_u32_e64 s[12:13], v122, v111
	v_add_f32_e32 v122, 1.0, v137
	v_rcp_f32_e32 v122, v122
	v_mul_f32_e32 v136, v136, v121
	v_mfma_f32_16x16x32_bf16 v[128:131], v[152:155], v[12:15], v[128:131]
	s_nop 0
	v_mov_b32_e32 v123, v136
	v_mul_f32_e32 v136, v137, v122
	v_exp_f32_e32 v137, v125
	v_cndmask_b32_e64 v144, 0, v123, s[12:13]
	v_add_u32_e32 v123, 0x44, v99
	v_cndmask_b32_e64 v121, 1.0, v121, s[12:13]
	v_cmp_lt_u32_e64 s[12:13], v123, v111
	v_add_f32_e32 v123, 1.0, v137
	v_rcp_f32_e32 v123, v123
	v_exp_f32_e32 v138, v128
	v_exp_f32_e32 v139, v131
	v_mov_b32_e32 v124, v136
	v_mul_f32_e32 v136, v137, v123
	v_exp_f32_e32 v137, v126
	v_cndmask_b32_e64 v145, 0, v124, s[12:13]
	v_add_u32_e32 v124, 0x45, v99
	v_cndmask_b32_e64 v122, 1.0, v122, s[12:13]
	v_cmp_lt_u32_e64 s[12:13], v124, v111
	v_add_f32_e32 v124, 1.0, v137
	v_rcp_f32_e32 v124, v124
	s_waitcnt lgkmcnt(0)
	v_mfma_f32_16x16x32_bf16 v[132:135], v[164:167], v[12:15], v[132:135]
	v_mov_b32_e32 v125, v136
	v_mul_f32_e32 v136, v137, v124
	v_exp_f32_e32 v137, v127
	v_cndmask_b32_e64 v146, 0, v125, s[12:13]
	v_add_u32_e32 v125, 0x46, v99
	v_cndmask_b32_e64 v123, 1.0, v123, s[12:13]
	v_cmp_lt_u32_e64 s[12:13], v125, v111
	v_mov_b32_e32 v126, v136
	v_add_f32_e32 v125, 1.0, v137
	v_add_u32_e32 v136, 0x47, v99
	v_cndmask_b32_e64 v126, 0, v126, s[12:13]
	v_rcp_f32_e32 v125, v125
	v_cndmask_b32_e64 v124, 1.0, v124, s[12:13]
	v_cmp_lt_u32_e64 s[12:13], v136, v111
	v_add_f32_e32 v136, 1.0, v138
	v_rcp_f32_e32 v136, v136
	v_mul_f32_e32 v137, v137, v125
	s_nop 1
	v_mov_b32_e32 v127, v137
	v_mul_f32_e32 v137, v138, v136
	v_exp_f32_e32 v138, v129
	v_cndmask_b32_e64 v147, 1.0, v125, s[12:13]
	v_add_u32_e32 v125, 0x60, v99
	v_cndmask_b32_e64 v127, 0, v127, s[12:13]
	v_cmp_lt_u32_e64 s[12:13], v125, v111
	v_add_f32_e32 v125, 1.0, v138
	v_rcp_f32_e32 v125, v125
	v_mul_f32_e32 v153, v147, v124
	v_mul_f32_e32 v154, v123, v153
	v_mov_b32_e32 v128, v137
	v_mul_f32_e32 v137, v138, v125
	v_exp_f32_e32 v138, v130
	v_cndmask_b32_e64 v140, 1.0, v136, s[12:13]
	v_add_u32_e32 v136, 0x61, v99
	v_cndmask_b32_e64 v128, 0, v128, s[12:13]
	v_cmp_lt_u32_e64 s[12:13], v136, v111
	v_mov_b32_e32 v129, v137
	v_add_f32_e32 v136, 1.0, v138
	v_add_u32_e32 v137, 0x62, v99
	v_cndmask_b32_e64 v129, 0, v129, s[12:13]
	v_rcp_f32_e32 v136, v136
	v_cndmask_b32_e64 v125, 1.0, v125, s[12:13]
	v_cmp_lt_u32_e64 s[12:13], v137, v111
	v_add_f32_e32 v137, 1.0, v139
	v_rcp_f32_e32 v137, v137
	v_mul_f32_e32 v138, v138, v136
	v_mul_f32_e32 v155, v122, v154
; #define LAS __attribute__((address_space(3)))
; __device__ __forceinline__ void attn_unit(LAS unsigned char* lds, const bf16_t* Qm, const bf16_t* Km, const bf16_t* VT, const bf16_t* GBm, bf16_t* YB, int b, int hp, int qb) {
;     ...
;             for (int c = 0; c < 2; ++c)
; #pragma unroll
;                 for (int i = 0; i < 8; ++i) {
;                     const float z = s[2 * c + (i >> 2)][i & 3];
;                     const int key = k0 + 32 * c + 8 * fq + i;
;                     const float e = __builtin_amdgcn_exp2f(-fabsf(z));
;                     const float r = __builtin_amdgcn_rcpf(1.0f + e);
;                     const bool pos = z >= 0.f, valid = key < qi;
;                     be[c][i] = valid ? (pos ? r : e * r) : 0.f;
;                     om[c][i] = valid ? (pos ? e * r : r) : 1.f;
;                 }
;             float suf[2][8], Gs[2], Tt[2];
; #pragma unroll
;             for (int c = 0; c < 2; ++c) {
;                 float run = 1.f;
; #pragma unroll
;                 for (int i = 7; i >= 0; --i) { suf[c][i] = run; run *= om[c][i]; }
;                 const float t1 = __shfl(run, (lane + 16) & 63), t2 = __shfl(run, (lane + 32) & 63), t3 = __shfl(run, (lane + 48) & 63);
;                 Gs[c] = (fq < 3 ? t1 : 1.f) * (fq < 2 ? t2 : 1.f) * (fq < 1 ? t3 : 1.f);
;                 Tt[c] = (run * t1) * (t2 * t3);
;             }
;             bf16x8 pf[2];
; #pragma unroll
;             for (int c = 0; c < 2; ++c) {
;                 const float basec = Rs * Gs[c] * (c == 0 ? Tt[1] : 1.f);
;                 float w[8];
; #pragma unroll
;                 for (int i = 0; i < 8; ++i) w[i] = be[c][i] * (suf[c][i] * basec);
;                 u32x4 pw; pw.x = cvt_pk_bf16(w[0], w[1]); pw.y = cvt_pk_bf16(w[2], w[3]); pw.z = cvt_pk_bf16(w[4], w[5]); pw.w = cvt_pk_bf16(w[6], w[7]);
;                 pf[c] = __builtin_bit_cast(bf16x8, pw);
;             }
;             Rs *= Tt[0] * Tt[1];
; #pragma unroll
;             for (int db = 0; db < 8; ++db)
; #pragma unroll
;                 for (int c = 0; c < 2; ++c) {
;                     const bf16x8 a = *(const LAS bf16x8*)(VL + (db * 16 + fr) * 144 + (32 * c + 8 * fq) * 2);
;                     o[db] = __builtin_amdgcn_mfma_f32_16x16x32_bf16(a, pf[c], o[db], 0, 0, 0);
;                 }
	v_mul_f32_e32 v156, v121, v155
	v_mov_b32_e32 v130, v138
	v_mul_f32_e32 v138, v139, v137
	v_exp_f32_e32 v139, v132
	v_cndmask_b32_e64 v141, 1.0, v136, s[12:13]
	v_add_u32_e32 v136, 0x63, v99
	v_cndmask_b32_e64 v130, 0, v130, s[12:13]
	v_cmp_lt_u32_e64 s[12:13], v136, v111
	v_add_f32_e32 v136, 1.0, v139
	v_rcp_f32_e32 v136, v136
	v_mul_f32_e32 v157, v120, v156
	v_mul_f32_e32 v103, v103, v157
	v_mov_b32_e32 v131, v138
	v_mul_f32_e32 v138, v139, v136
	v_exp_f32_e32 v139, v133
	v_cndmask_b32_e64 v148, 1.0, v137, s[12:13]
	v_add_u32_e32 v137, 0x64, v99
	v_cndmask_b32_e64 v131, 0, v131, s[12:13]
	v_cmp_lt_u32_e64 s[12:13], v137, v111
	v_add_f32_e32 v137, 1.0, v139
	v_rcp_f32_e32 v137, v137
	s_nop 1
	v_mov_b32_e32 v132, v138
	v_mul_f32_e32 v138, v139, v137
	v_exp_f32_e32 v139, v134
	v_cndmask_b32_e64 v149, 1.0, v136, s[12:13]
	v_add_u32_e32 v136, 0x65, v99
	v_cndmask_b32_e64 v132, 0, v132, s[12:13]
	v_cmp_lt_u32_e64 s[12:13], v136, v111
	v_add_f32_e32 v136, 1.0, v139
	v_rcp_f32_e32 v136, v136
	s_nop 1
	v_mov_b32_e32 v133, v138
	v_mul_f32_e32 v138, v139, v136
	v_exp_f32_e32 v139, v135
	v_cndmask_b32_e64 v150, 1.0, v137, s[12:13]
	v_add_u32_e32 v137, 0x66, v99
	v_cndmask_b32_e64 v133, 0, v133, s[12:13]
	v_cmp_lt_u32_e64 s[12:13], v137, v111
	v_add_f32_e32 v137, 1.0, v139
	v_rcp_f32_e32 v151, v137
	v_add_u32_e32 v99, 0x67, v99
	v_mul_f32_e32 v139, v139, v151
	v_cndmask_b32_e64 v134, 0, v138, s[12:13]
	v_cndmask_b32_e64 v152, 1.0, v136, s[12:13]
	v_cmp_lt_u32_e64 s[12:13], v99, v111
	v_mul_f32_e32 v136, v97, v103
	s_nop 0
	v_cndmask_b32_e64 v99, 0, v139, s[12:13]
	v_or_b32_e32 v135, v105, v107
	v_lshlrev_b32_e32 v135, 2, v135
	v_cndmask_b32_e64 v151, 1.0, v151, s[12:13]
	v_xor_b32_e32 v135, 0x80, v135
	v_mul_f32_e32 v152, v151, v152
	ds_bpermute_b32 v137, v135, v136
	ds_bpermute_b32 v138, v118, v136
	v_mul_f32_e32 v150, v150, v152
	v_mul_f32_e32 v149, v149, v150
	v_mul_f32_e32 v148, v148, v149
	v_mul_f32_e32 v158, v141, v148
	v_mul_f32_e32 v159, v125, v158
	ds_bpermute_b32 v139, v119, v136
	s_waitcnt lgkmcnt(2)
	v_cndmask_b32_e64 v97, 1.0, v137, s[10:11]
	s_waitcnt lgkmcnt(1)
	v_cndmask_b32_e64 v120, v138, 1.0, s[0:1]
	v_mul_f32_e32 v121, v140, v159
	v_mul_f32_e32 v97, v120, v97
	ds_bpermute_b32 v120, v135, v121
	ds_bpermute_b32 v123, v118, v121
	ds_bpermute_b32 v122, v119, v121
	s_waitcnt lgkmcnt(3)
	v_cndmask_b32_e64 v124, 1.0, v139, s[4:5]
	v_mul_f32_e32 v124, v97, v124
	s_waitcnt lgkmcnt(2)
	v_cndmask_b32_e64 v97, 1.0, v120, s[10:11]
	s_waitcnt lgkmcnt(1)
	v_cndmask_b32_e64 v125, v123, 1.0, s[0:1]
	v_mul_f32_e32 v97, v125, v97
	s_waitcnt lgkmcnt(0)
	v_cndmask_b32_e64 v125, 1.0, v122, s[4:5]
	v_pk_mul_f32 v[120:121], v[120:121], v[122:123]
	v_mul_f32_e32 v135, v97, v125
	v_mov_b32_e32 v97, v120
	v_mov_b32_e32 v125, v121
	v_pk_mul_f32 v[140:141], v[96:97], v[124:125]
	s_nop 0
	v_mul_f32_e32 v97, v140, v141
	v_mul_f32_e32 v120, v156, v97
	v_mul_f32_e32 v121, v143, v120
	v_mul_f32_e32 v120, v155, v97
	v_mul_f32_e32 v122, v144, v120
	v_mul_f32_e32 v120, v154, v97
	v_mul_f32_e32 v103, v103, v97
	v_mul_f32_e32 v123, v145, v120
	v_mul_f32_e32 v120, v153, v97
	v_mul_f32_e32 v101, v101, v103
	v_mul_f32_e32 v103, v157, v97
	v_mul_f32_e32 v124, v146, v120
	v_mul_f32_e32 v120, v147, v97
	v_mul_f32_e32 v97, v127, v97
	v_mul_f32_e32 v103, v142, v103
	v_mul_f32_e32 v125, v126, v120
	v_cvt_pk_bf16_f32 v120, v101, v103
	v_cvt_pk_bf16_f32 v121, v121, v122
	v_cvt_pk_bf16_f32 v122, v123, v124
	v_cvt_pk_bf16_f32 v123, v125, v97
	v_mul_f32_e32 v97, v96, v135
	v_mul_f32_e32 v124, v97, v148
	v_mul_f32_e32 v125, v130, v124
	v_mul_f32_e32 v124, v97, v149
	v_mul_f32_e32 v126, v131, v124
	v_mul_f32_e32 v124, v97, v150
	v_mul_f32_e32 v101, v97, v159
	v_mul_f32_e32 v127, v132, v124
	v_mul_f32_e32 v124, v97, v152
	v_mul_f32_e32 v101, v128, v101
	v_mul_f32_e32 v103, v97, v158
	v_mul_f32_e32 v128, v133, v124
	v_mul_f32_e32 v124, v151, v97
	v_mul_f32_e32 v103, v129, v103
	v_mul_f32_e32 v129, v134, v124
	v_mul_f32_e32 v97, v99, v97
	v_cvt_pk_bf16_f32 v124, v101, v103
	v_cvt_pk_bf16_f32 v125, v125, v126
	v_cvt_pk_bf16_f32 v126, v127, v128
	v_cvt_pk_bf16_f32 v127, v129, v97
	ds_read_b128 v[128:131], v117 offset:17408
	ds_read_b128 v[132:135], v117 offset:17472
	s_waitcnt lgkmcnt(1)
	v_mfma_f32_16x16x32_bf16 v[60:63], v[128:131], v[120:123], v[60:63]
	ds_read_b128 v[128:131], v117 offset:19712
	s_waitcnt lgkmcnt(1)
	v_mfma_f32_16x16x32_bf16 v[60:63], v[132:135], v[124:127], v[60:63]
	ds_read_b128 v[132:135], v117 offset:19776
	s_waitcnt lgkmcnt(1)
	v_mfma_f32_16x16x32_bf16 v[72:75], v[128:131], v[120:123], v[72:75]
	ds_read_b128 v[128:131], v117 offset:22016
	s_waitcnt lgkmcnt(1)
	v_mfma_f32_16x16x32_bf16 v[72:75], v[132:135], v[124:127], v[72:75]
	ds_read_b128 v[132:135], v117 offset:22080
	s_waitcnt lgkmcnt(1)
	v_mfma_f32_16x16x32_bf16 v[56:59], v[128:131], v[120:123], v[56:59]
	ds_read_b128 v[128:131], v117 offset:24320
	s_waitcnt lgkmcnt(1)
	v_mfma_f32_16x16x32_bf16 v[56:59], v[132:135], v[124:127], v[56:59]
	ds_read_b128 v[132:135], v117 offset:24384
	s_waitcnt lgkmcnt(1)
	v_mfma_f32_16x16x32_bf16 v[44:47], v[128:131], v[120:123], v[44:47]
	ds_read_b128 v[128:131], v117 offset:26624
	s_waitcnt lgkmcnt(1)
	v_mfma_f32_16x16x32_bf16 v[44:47], v[132:135], v[124:127], v[44:47]
	ds_read_b128 v[132:135], v117 offset:26688
	s_waitcnt lgkmcnt(1)
	v_mfma_f32_16x16x32_bf16 v[32:35], v[128:131], v[120:123], v[32:35]
	ds_read_b128 v[128:131], v117 offset:28928
	s_waitcnt lgkmcnt(1)
	v_mfma_f32_16x16x32_bf16 v[32:35], v[132:135], v[124:127], v[32:35]
	ds_read_b128 v[132:135], v117 offset:28992
	s_waitcnt lgkmcnt(1)
	v_mfma_f32_16x16x32_bf16 v[24:27], v[128:131], v[120:123], v[24:27]
	ds_read_b128 v[128:131], v117 offset:31232
	s_waitcnt lgkmcnt(1)
	v_mfma_f32_16x16x32_bf16 v[24:27], v[132:135], v[124:127], v[24:27]
	ds_read_b128 v[132:135], v117 offset:31296
	s_waitcnt lgkmcnt(1)
	v_mfma_f32_16x16x32_bf16 v[20:23], v[128:131], v[120:123], v[20:23]
	ds_read_b128 v[128:131], v117 offset:33536
	s_waitcnt lgkmcnt(1)
	v_mfma_f32_16x16x32_bf16 v[20:23], v[132:135], v[124:127], v[20:23]
	ds_read_b128 v[132:135], v117 offset:33600
	s_waitcnt lgkmcnt(1)
	v_mfma_f32_16x16x32_bf16 v[16:19], v[128:131], v[120:123], v[16:19]
	v_mul_f32_e64 v120, v136, v138
	v_mul_f32_e64 v121, v137, v139
	v_mul_f32_e32 v97, v120, v121
	s_waitcnt lgkmcnt(0)
	v_mfma_f32_16x16x32_bf16 v[16:19], v[132:135], v[124:127], v[16:19]
	v_mul_f32_e32 v97, v97, v141
	v_mul_f32_e32 v96, v96, v97
